# prologue scaled weight transposes (two inlined copies): 8 weight loads + 8 row-scale loads per trip issued together, one wait (were issued one or two at a time)
# speedup vs baseline: 1.0109x; 1.0003x over previous
; __device__ __forceinline__ void tr_item(const float* W, int ldw, int ncols, bf16* WT, int ldt, int row_off, float* scr, int item, int lane, const float* kscale) {
;     const int nblk = ncols / 32, kb = item / nblk, nb = item % nblk, k0 = 64 * kb, n0 = 32 * nb;
; #pragma unroll 8
;     for (int i = 0; i < 32; ++i) { const int kk = 2 * i + (lane >> 5); float v = W[(size_t)(k0 + kk) * ldw + n0 + (lane & 31)]; if (kscale) v *= kscale[k0 + kk]; scr[kk * 33 + (lane & 31)] = v; }
;     asm volatile("s_waitcnt lgkmcnt(0)" ::: "memory");
.LBB0_1252:
	v_lshl_add_u64 v[96:97], v[2:3], 0, s[12:13]
	global_load_dword v112, v[96:97], off
	v_lshl_add_u64 v[98:99], v[16:17], 0, s[12:13]
	global_load_dword v113, v[98:99], off
	v_lshl_add_u64 v[100:101], v[14:15], 0, s[12:13]
	global_load_dword v114, v[100:101], off
	v_lshl_add_u64 v[102:103], v[12:13], 0, s[12:13]
	global_load_dword v115, v[102:103], off
	v_lshl_add_u64 v[104:105], v[10:11], 0, s[12:13]
	global_load_dword v116, v[104:105], off
	v_lshl_add_u64 v[106:107], v[8:9], 0, s[12:13]
	global_load_dword v117, v[106:107], off
	v_lshl_add_u64 v[108:109], v[4:5], 0, s[12:13]
	global_load_dword v118, v[108:109], off
	v_lshl_add_u64 v[110:111], v[0:1], 0, s[12:13]
	global_load_dword v119, v[110:111], off
	s_andn2_b64 vcc, exec, s[14:15]
	s_cbranch_vccnz .Lmy_tr1_ns
	global_load_dword v120, v[6:7], off offset:-56
	global_load_dword v121, v[6:7], off offset:-48
	global_load_dword v122, v[6:7], off offset:-40
	global_load_dword v123, v[6:7], off offset:-32
	global_load_dword v124, v[6:7], off offset:-24
	global_load_dword v125, v[6:7], off offset:-16
	global_load_dword v126, v[6:7], off offset:-8
	global_load_dword v127, v[6:7], off
	s_waitcnt vmcnt(0)
	v_mul_f32_e32 v112, v112, v120
	v_mul_f32_e32 v113, v113, v121
	v_mul_f32_e32 v114, v114, v122
	v_mul_f32_e32 v115, v115, v123
	v_mul_f32_e32 v116, v116, v124
	v_mul_f32_e32 v117, v117, v125
	v_mul_f32_e32 v118, v118, v126
	v_mul_f32_e32 v119, v119, v127
.Lmy_tr1_ns:
	s_waitcnt vmcnt(0)
	ds_write_b32 v18, v112
	ds_write_b32 v18, v113 offset:264
	ds_write_b32 v18, v114 offset:528
	ds_write_b32 v18, v115 offset:792
	ds_write_b32 v18, v116 offset:1056
	ds_write_b32 v18, v117 offset:1320
	ds_write_b32 v18, v118 offset:1584
	ds_write_b32 v18, v119 offset:1848
	s_add_u32 s12, s12, 0x8000
	s_addc_u32 s13, s13, 0
	v_add_u32_e32 v18, 0x840, v18
	v_lshl_add_u64 v[6:7], v[6:7], 0, 64
	s_cmp_lg_u32 s12, 0x20000
	s_cbranch_scc1 .LBB0_1252
	s_branch .LBB0_1269

; __device__ __forceinline__ void tr_item(const float* W, int ldw, int ncols, bf16* WT, int ldt, int row_off, float* scr, int item, int lane, const float* kscale) {
;     const int nblk = ncols / 32, kb = item / nblk, nb = item % nblk, k0 = 64 * kb, n0 = 32 * nb;
; #pragma unroll 8
;     for (int i = 0; i < 32; ++i) { const int kk = 2 * i + (lane >> 5); float v = W[(size_t)(k0 + kk) * ldw + n0 + (lane & 31)]; if (kscale) v *= kscale[k0 + kk]; scr[kk * 33 + (lane & 31)] = v; }
;     asm volatile("s_waitcnt lgkmcnt(0)" ::: "memory");
.LBB0_1274:
	v_lshl_add_u64 v[96:97], v[18:19], 0, s[8:9]
	global_load_dword v112, v[96:97], off
	v_lshl_add_u64 v[98:99], v[14:15], 0, s[8:9]
	global_load_dword v113, v[98:99], off
	v_lshl_add_u64 v[100:101], v[12:13], 0, s[8:9]
	global_load_dword v114, v[100:101], off
	v_lshl_add_u64 v[102:103], v[10:11], 0, s[8:9]
	global_load_dword v115, v[102:103], off
	v_lshl_add_u64 v[104:105], v[8:9], 0, s[8:9]
	global_load_dword v116, v[104:105], off
	v_lshl_add_u64 v[106:107], v[6:7], 0, s[8:9]
	global_load_dword v117, v[106:107], off
	v_lshl_add_u64 v[108:109], v[4:5], 0, s[8:9]
	global_load_dword v118, v[108:109], off
	v_lshl_add_u64 v[110:111], v[0:1], 0, s[8:9]
	global_load_dword v119, v[110:111], off
	s_andn2_b64 vcc, exec, s[10:11]
	s_cbranch_vccnz .Lmy_tr2_ns
	v_lshl_add_u64 v[128:129], v[16:17], 0, s[12:13]
	v_lshl_add_u64 v[130:131], v[2:3], 0, s[12:13]
	global_load_dword v120, v[128:129], off
	global_load_dword v121, v[130:131], off offset:8
	global_load_dword v122, v[130:131], off offset:16
	global_load_dword v123, v[130:131], off offset:24
	global_load_dword v124, v[130:131], off offset:32
	global_load_dword v125, v[130:131], off offset:40
	global_load_dword v126, v[130:131], off offset:48
	global_load_dword v127, v[130:131], off offset:56
	s_waitcnt vmcnt(0)
	v_mul_f32_e32 v112, v112, v120
	v_mul_f32_e32 v113, v113, v121
	v_mul_f32_e32 v114, v114, v122
	v_mul_f32_e32 v115, v115, v123
	v_mul_f32_e32 v116, v116, v124
	v_mul_f32_e32 v117, v117, v125
	v_mul_f32_e32 v118, v118, v126
	v_mul_f32_e32 v119, v119, v127
.Lmy_tr2_ns:
	s_waitcnt vmcnt(0)
	ds_write_b32 v22, v112
	ds_write_b32 v22, v113 offset:264
	ds_write_b32 v22, v114 offset:528
	ds_write_b32 v22, v115 offset:792
	ds_write_b32 v22, v116 offset:1056
	ds_write_b32 v22, v117 offset:1320
	ds_write_b32 v22, v118 offset:1584
	ds_write_b32 v22, v119 offset:1848
	s_add_u32 s8, s8, 0x6000
	s_addc_u32 s9, s9, 0
	v_add_u32_e32 v22, 0x840, v22
	v_lshl_add_u64 v[2:3], v[2:3], 0, 64
	v_lshl_add_u64 v[16:17], v[16:17], 0, 64
	s_cmp_lg_u32 s8, 0x18000
	s_cbranch_scc1 .LBB0_1274
	s_branch .LBB0_1290
